# grid barrier: all workgroups wait directly on the cross-XCD arrival counter (TOP >= (gen+1)*nx); TOPGEN/XGEN release chain and its round trips removed
# speedup vs baseline: 1.0105x; 1.0056x over previous
.LBB0_210:
	s_or_b64 exec, exec, s[6:7]
	v_cvt_f32_u32_e32 v4, v2
	s_waitcnt vmcnt(0)
	v_readfirstlane_b32 s0, v3
	v_sub_u32_e32 v3, 0, v2
	v_rcp_iflag_f32_e32 v4, v4
	v_add_u32_e32 v5, s0, v1
	v_mul_f32_e32 v4, 0x4f7ffffe, v4
	v_cvt_u32_f32_e32 v4, v4
	v_mul_lo_u32 v1, v3, v4
	v_mul_hi_u32 v1, v4, v1
	v_add_u32_e32 v1, v4, v1
	v_mul_hi_u32 v1, v5, v1
	v_mul_lo_u32 v3, v1, v2
	v_sub_u32_e32 v3, v5, v3
	v_add_u32_e32 v4, 1, v1
	v_sub_u32_e32 v6, v3, v2
	v_cmp_ge_u32_e32 vcc, v3, v2
	s_nop 1
	v_cndmask_b32_e32 v1, v1, v4, vcc
	v_cndmask_b32_e32 v3, v3, v6, vcc
	v_add_u32_e32 v4, 1, v1
	v_cmp_ge_u32_e32 vcc, v3, v2
	v_add_u32_e32 v3, 1, v5
	s_nop 0
	v_cndmask_b32_e32 v1, v1, v4, vcc
	v_mul_lo_u32 v4, v2, v1
	v_add_u32_e32 v2, v4, v2
	v_cmp_ne_u32_e32 vcc, v3, v2
	s_and_saveexec_b64 s[0:1], vcc
	s_xor_b64 s[8:9], exec, s[0:1]
	s_cbranch_execz .LBB0_224
	v_readlane_b32 s0, v239, 61
	v_readlane_b32 s1, v239, 62
	s_waitcnt lgkmcnt(0)
	s_nop 3
	s_waitcnt lgkmcnt(0)
	v_mad_u32_u24 v254, v1, v0, v0
	global_load_dword v0, v165, s[0:1] sc1
	s_waitcnt vmcnt(0)
	v_cmp_lt_u32_e32 vcc, v0, v254
	s_and_saveexec_b64 s[10:11], vcc
	s_cbranch_execz .LBB0_223
	s_mov_b32 s0, 1
	s_mov_b64 s[12:13], 0
	s_branch .LBB0_214

.LBB0_218:
	v_readlane_b32 s6, v239, 61
	v_readlane_b32 s7, v239, 62
	s_add_i32 s0, s0, 1
	s_mov_b64 s[20:21], -1
	s_nop 2
	global_load_dword v0, v165, s[6:7] sc1
	s_waitcnt vmcnt(0)
	v_cmp_ge_u32_e32 vcc, v0, v254
	s_orn2_b64 s[16:17], vcc, exec
	s_branch .LBB0_213

.LBB0_227:
	s_or_b64 exec, exec, s[8:9]
	v_cvt_f32_u32_e32 v3, v0
	s_waitcnt vmcnt(0)
	v_readfirstlane_b32 s0, v2
	v_sub_u32_e32 v2, 0, v0
	s_mov_b64 s[10:11], 0
	v_rcp_iflag_f32_e32 v3, v3
	v_add_u32_e32 v1, s0, v1
	v_add_u32_e32 v4, 1, v1
	v_readlane_b32 s0, v239, 63
	v_mul_f32_e32 v3, 0x4f7ffffe, v3
	v_cvt_u32_f32_e32 v3, v3
	v_readlane_b32 s1, v238, 0
	v_mul_lo_u32 v2, v2, v3
	v_mul_hi_u32 v2, v3, v2
	v_add_u32_e32 v2, v3, v2
	v_mul_hi_u32 v2, v1, v2
	v_mul_lo_u32 v3, v2, v0
	v_sub_u32_e32 v1, v1, v3
	v_add_u32_e32 v5, 1, v2
	v_sub_u32_e32 v3, v1, v0
	v_cmp_ge_u32_e32 vcc, v1, v0
	s_nop 1
	v_cndmask_b32_e32 v2, v2, v5, vcc
	v_cndmask_b32_e32 v1, v1, v3, vcc
	v_add_u32_e32 v3, 1, v2
	v_cmp_ge_u32_e32 vcc, v1, v0
	s_nop 1
	v_cndmask_b32_e32 v2, v2, v3, vcc
	v_mul_lo_u32 v1, v0, v2
	v_add_u32_e32 v0, v1, v0
	v_mov_b32_e32 v255, v0
	v_cmp_ne_u32_e32 vcc, v4, v0
	v_mov_b64_e32 v[0:1], s[0:1]
	s_and_saveexec_b64 s[8:9], vcc
	s_cbranch_execz .LBB0_239
	v_readlane_b32 s0, v239, 61
	v_readlane_b32 s1, v239, 62
	s_mov_b64 s[6:7], 0
	s_nop 3
	global_load_dword v0, v165, s[0:1] sc1
	s_waitcnt vmcnt(0)
	v_cmp_lt_u32_e32 vcc, v0, v255
	s_and_saveexec_b64 s[10:11], vcc
	s_cbranch_execz .LBB0_238
	s_mov_b32 s0, 1
	s_mov_b64 s[12:13], 0
	s_branch .LBB0_231

.LBB0_235:
	v_readlane_b32 s6, v239, 61
	v_readlane_b32 s7, v239, 62
	s_add_i32 s0, s0, 1
	s_mov_b64 s[20:21], -1
	s_nop 2
	global_load_dword v0, v165, s[6:7] sc1
	s_waitcnt vmcnt(0)
	v_cmp_ge_u32_e32 vcc, v0, v255
	s_orn2_b64 s[16:17], vcc, exec
	s_branch .LBB0_230

.LBB0_241:
	s_or_b64 exec, exec, s[6:7]
	s_mov_b64 s[6:7], exec
	v_mbcnt_lo_u32_b32 v0, s6, 0
	v_mbcnt_hi_u32_b32 v0, s7, v0
	v_cmp_eq_u32_e32 vcc, 0, v0
	s_waitcnt vmcnt(0)
	buffer_inv sc1
	s_and_saveexec_b64 s[8:9], vcc
	s_cbranch_execz .LBB0_243
	s_bcnt1_i32_b64 s0, s[6:7]
	v_mov_b32_e32 v0, s0
	v_readlane_b32 s0, v239, 59
	v_readlane_b32 s1, v239, 60
	s_nop 4
.LBB0_243:
	s_or_b64 exec, exec, s[8:9]
	s_waitcnt vmcnt(0)

.LBB0_408:
	s_or_b64 exec, exec, s[6:7]
	v_cvt_f32_u32_e32 v4, v2
	s_waitcnt vmcnt(0)
	v_readfirstlane_b32 s0, v3
	v_sub_u32_e32 v3, 0, v2
	v_rcp_iflag_f32_e32 v4, v4
	v_add_u32_e32 v5, s0, v1
	v_mul_f32_e32 v4, 0x4f7ffffe, v4
	v_cvt_u32_f32_e32 v4, v4
	v_mul_lo_u32 v1, v3, v4
	v_mul_hi_u32 v1, v4, v1
	v_add_u32_e32 v1, v4, v1
	v_mul_hi_u32 v1, v5, v1
	v_mul_lo_u32 v3, v1, v2
	v_sub_u32_e32 v3, v5, v3
	v_add_u32_e32 v4, 1, v1
	v_cmp_ge_u32_e32 vcc, v3, v2
	s_nop 1
	v_cndmask_b32_e32 v1, v1, v4, vcc
	v_sub_u32_e32 v4, v3, v2
	v_cndmask_b32_e32 v3, v3, v4, vcc
	v_add_u32_e32 v4, 1, v1
	v_cmp_ge_u32_e32 vcc, v3, v2
	v_add_u32_e32 v3, 1, v5
	s_nop 0
	v_cndmask_b32_e32 v1, v1, v4, vcc
	v_mul_lo_u32 v4, v2, v1
	v_add_u32_e32 v2, v4, v2
	v_cmp_ne_u32_e32 vcc, v3, v2
	s_and_saveexec_b64 s[0:1], vcc
	s_xor_b64 s[8:9], exec, s[0:1]
	s_cbranch_execz .LBB0_422
	v_readlane_b32 s0, v239, 61
	v_readlane_b32 s1, v239, 62
	s_waitcnt lgkmcnt(0)
	s_nop 3
	s_waitcnt lgkmcnt(0)
	v_mad_u32_u24 v254, v1, v0, v0
	global_load_dword v0, v165, s[0:1] sc1
	s_waitcnt vmcnt(0)
	v_cmp_lt_u32_e32 vcc, v0, v254
	s_and_saveexec_b64 s[10:11], vcc
	s_cbranch_execz .LBB0_421
	s_mov_b32 s0, 1
	s_mov_b64 s[12:13], 0
	s_branch .LBB0_412

.LBB0_425:
	s_or_b64 exec, exec, s[8:9]
	s_waitcnt vmcnt(0)
	v_readfirstlane_b32 s0, v2
	v_cvt_f32_u32_e32 v2, v0
	v_sub_u32_e32 v3, 0, v0
	v_add_u32_e32 v1, s0, v1
	v_readlane_b32 s0, v239, 63
	v_rcp_iflag_f32_e32 v2, v2
	v_readlane_b32 s1, v238, 0
	s_mov_b64 s[10:11], 0
	v_mul_f32_e32 v2, 0x4f7ffffe, v2
	v_cvt_u32_f32_e32 v2, v2
	v_mul_lo_u32 v3, v3, v2
	v_mul_hi_u32 v3, v2, v3
	v_add_u32_e32 v2, v2, v3
	v_mul_hi_u32 v2, v1, v2
	v_mul_lo_u32 v3, v2, v0
	v_sub_u32_e32 v3, v1, v3
	v_cmp_ge_u32_e32 vcc, v3, v0
	v_add_u32_e32 v4, 1, v2
	v_add_u32_e32 v1, 1, v1
	v_cndmask_b32_e32 v2, v2, v4, vcc
	v_sub_u32_e32 v4, v3, v0
	v_cndmask_b32_e32 v3, v3, v4, vcc
	v_cmp_ge_u32_e32 vcc, v3, v0
	v_add_u32_e32 v3, 1, v2
	s_nop 0
	v_cndmask_b32_e32 v2, v2, v3, vcc
	v_mul_lo_u32 v3, v0, v2
	v_add_u32_e32 v0, v3, v0
	v_mov_b32_e32 v255, v0
	v_cmp_ne_u32_e32 vcc, v1, v0
	v_mov_b64_e32 v[0:1], s[0:1]
	s_and_saveexec_b64 s[8:9], vcc
	s_cbranch_execz .LBB0_437
	v_readlane_b32 s0, v239, 61
	v_readlane_b32 s1, v239, 62
	s_mov_b64 s[6:7], 0
	s_nop 3
	global_load_dword v0, v165, s[0:1] sc1
	s_waitcnt vmcnt(0)
	v_cmp_lt_u32_e32 vcc, v0, v255
	s_and_saveexec_b64 s[10:11], vcc
	s_cbranch_execz .LBB0_436
	s_mov_b32 s0, 1
	s_mov_b64 s[12:13], 0
	s_branch .LBB0_429

.LBB0_439:
	s_or_b64 exec, exec, s[6:7]
	s_mov_b64 s[6:7], exec
	v_mbcnt_lo_u32_b32 v0, s6, 0
	v_mbcnt_hi_u32_b32 v0, s7, v0
	v_cmp_eq_u32_e32 vcc, 0, v0
	s_waitcnt vmcnt(0)
	buffer_inv sc1
	s_and_saveexec_b64 s[8:9], vcc
	s_cbranch_execz .LBB0_441
	s_bcnt1_i32_b64 s0, s[6:7]
	v_mov_b32_e32 v0, s0
	v_readlane_b32 s0, v239, 59
	v_readlane_b32 s1, v239, 60
	s_nop 4
.LBB0_441:
	s_or_b64 exec, exec, s[8:9]
	s_waitcnt vmcnt(0)

.LBB0_515:
	s_or_b64 exec, exec, s[6:7]
	s_mov_b64 s[6:7], exec
	v_mbcnt_lo_u32_b32 v0, s6, 0
	v_mbcnt_hi_u32_b32 v0, s7, v0
	v_cmp_eq_u32_e32 vcc, 0, v0
	s_waitcnt vmcnt(0)
	buffer_inv sc1
	s_and_saveexec_b64 s[8:9], vcc
	s_cbranch_execz .LBB0_517
	s_bcnt1_i32_b64 s0, s[6:7]
	v_mov_b32_e32 v0, s0
	v_readlane_b32 s0, v239, 59
	v_readlane_b32 s1, v239, 60
	s_nop 4
.LBB0_517:
	s_or_b64 exec, exec, s[8:9]
	s_waitcnt vmcnt(0)

.LBB0_612:
	s_or_b64 exec, exec, s[6:7]
	s_mov_b64 s[6:7], exec
	v_mbcnt_lo_u32_b32 v0, s6, 0
	v_mbcnt_hi_u32_b32 v0, s7, v0
	v_cmp_eq_u32_e32 vcc, 0, v0
	s_waitcnt vmcnt(0)
	buffer_inv sc1
	s_and_saveexec_b64 s[8:9], vcc
	s_cbranch_execz .LBB0_614
	s_bcnt1_i32_b64 s0, s[6:7]
	v_mov_b32_e32 v0, s0
	v_readlane_b32 s0, v239, 59
	v_readlane_b32 s1, v239, 60
	s_nop 4
.LBB0_614:
	s_or_b64 exec, exec, s[8:9]
	s_waitcnt vmcnt(0)

.LBB0_681:
	s_or_b64 exec, exec, s[6:7]
	s_mov_b64 s[6:7], exec
	v_mbcnt_lo_u32_b32 v0, s6, 0
	v_mbcnt_hi_u32_b32 v0, s7, v0
	v_cmp_eq_u32_e32 vcc, 0, v0
	s_waitcnt vmcnt(0)
	buffer_inv sc1
	s_and_saveexec_b64 s[8:9], vcc
	s_cbranch_execz .LBB0_683
	s_bcnt1_i32_b64 s0, s[6:7]
	v_mov_b32_e32 v0, s0
	v_readlane_b32 s0, v239, 59
	v_readlane_b32 s1, v239, 60
	s_nop 4
.LBB0_683:
	s_or_b64 exec, exec, s[8:9]
	s_waitcnt vmcnt(0)

.LBB0_773:
	s_or_b64 exec, exec, s[6:7]
	s_mov_b64 s[6:7], exec
	v_mbcnt_lo_u32_b32 v0, s6, 0
	v_mbcnt_hi_u32_b32 v0, s7, v0
	v_cmp_eq_u32_e32 vcc, 0, v0
	s_waitcnt vmcnt(0)
	buffer_inv sc1
	s_and_saveexec_b64 s[8:9], vcc
	s_cbranch_execz .LBB0_775
	s_bcnt1_i32_b64 s0, s[6:7]
	v_mov_b32_e32 v0, s0
	v_readlane_b32 s0, v239, 59
	v_readlane_b32 s1, v239, 60
	s_nop 4
.LBB0_775:
	s_or_b64 exec, exec, s[8:9]
	s_waitcnt vmcnt(0)

.LBB0_855:
	s_or_b64 exec, exec, s[6:7]
	s_mov_b64 s[6:7], exec
	v_mbcnt_lo_u32_b32 v0, s6, 0
	v_mbcnt_hi_u32_b32 v0, s7, v0
	v_cmp_eq_u32_e32 vcc, 0, v0
	s_waitcnt vmcnt(0)
	buffer_inv sc1
	s_and_saveexec_b64 s[8:9], vcc
	s_cbranch_execz .LBB0_857
	s_bcnt1_i32_b64 s0, s[6:7]
	v_mov_b32_e32 v0, s0
	v_readlane_b32 s0, v239, 59
	v_readlane_b32 s1, v239, 60
	s_nop 4
.LBB0_857:
	s_or_b64 exec, exec, s[8:9]
	s_waitcnt vmcnt(0)

.LBB0_953:
	s_or_b64 exec, exec, s[6:7]
	s_mov_b64 s[6:7], exec
	v_mbcnt_lo_u32_b32 v0, s6, 0
	v_mbcnt_hi_u32_b32 v0, s7, v0
	v_cmp_eq_u32_e32 vcc, 0, v0
	s_waitcnt vmcnt(0)
	buffer_inv sc1
	s_and_saveexec_b64 s[8:9], vcc
	s_cbranch_execz .LBB0_955
	s_bcnt1_i32_b64 s0, s[6:7]
	v_mov_b32_e32 v0, s0
	v_readlane_b32 s0, v239, 59
	v_readlane_b32 s1, v239, 60
	s_nop 4
.LBB0_955:
	s_or_b64 exec, exec, s[8:9]
	s_waitcnt vmcnt(0)

.LBB0_1188:
	s_or_b64 exec, exec, s[6:7]
	s_mov_b64 s[6:7], exec
	v_mbcnt_lo_u32_b32 v0, s6, 0
	v_mbcnt_hi_u32_b32 v0, s7, v0
	v_cmp_eq_u32_e32 vcc, 0, v0
	s_waitcnt vmcnt(0)
	buffer_inv sc1
	s_and_saveexec_b64 s[8:9], vcc
	s_cbranch_execz .LBB0_1190
	s_bcnt1_i32_b64 s0, s[6:7]
	v_mov_b32_e32 v0, s0
	v_readlane_b32 s0, v239, 59
	v_readlane_b32 s1, v239, 60
	s_nop 4
.LBB0_1190:
	s_or_b64 exec, exec, s[8:9]
	s_waitcnt vmcnt(0)

.LBB0_1243:
	s_or_b64 exec, exec, s[6:7]
	s_mov_b64 s[6:7], exec
	v_mbcnt_lo_u32_b32 v0, s6, 0
	v_mbcnt_hi_u32_b32 v0, s7, v0
	v_cmp_eq_u32_e32 vcc, 0, v0
	s_waitcnt vmcnt(0)
	buffer_inv sc1
	s_and_saveexec_b64 s[8:9], vcc
	s_cbranch_execz .LBB0_1245
	s_bcnt1_i32_b64 s0, s[6:7]
	v_mov_b32_e32 v0, s0
	v_readlane_b32 s0, v239, 59
	v_readlane_b32 s1, v239, 60
	s_nop 4
.LBB0_1245:
	s_or_b64 exec, exec, s[8:9]
	s_waitcnt vmcnt(0)

.LBB0_1294:
	s_or_b64 exec, exec, s[4:5]
	v_cvt_f32_u32_e32 v4, v2
	s_waitcnt vmcnt(0)
	v_readfirstlane_b32 s2, v3
	v_sub_u32_e32 v3, 0, v2
	v_rcp_iflag_f32_e32 v4, v4
	v_add_u32_e32 v5, s2, v1
	v_mul_f32_e32 v4, 0x4f7ffffe, v4
	v_cvt_u32_f32_e32 v4, v4
	v_mul_lo_u32 v1, v3, v4
	v_mul_hi_u32 v1, v4, v1
	v_add_u32_e32 v1, v4, v1
	v_mul_hi_u32 v1, v5, v1
	v_mul_lo_u32 v3, v1, v2
	v_sub_u32_e32 v3, v5, v3
	v_add_u32_e32 v4, 1, v1
	v_cmp_ge_u32_e32 vcc, v3, v2
	s_nop 1
	v_cndmask_b32_e32 v1, v1, v4, vcc
	v_sub_u32_e32 v4, v3, v2
	v_cndmask_b32_e32 v3, v3, v4, vcc
	v_add_u32_e32 v4, 1, v1
	v_cmp_ge_u32_e32 vcc, v3, v2
	v_add_u32_e32 v3, 1, v5
	s_nop 0
	v_cndmask_b32_e32 v1, v1, v4, vcc
	v_mul_lo_u32 v4, v2, v1
	v_add_u32_e32 v2, v4, v2
	v_cmp_ne_u32_e32 vcc, v3, v2
	s_and_saveexec_b64 s[4:5], vcc
	s_xor_b64 s[4:5], exec, s[4:5]
	s_cbranch_execz .LBB0_1308
	v_readlane_b32 s6, v239, 61
	v_readlane_b32 s7, v239, 62
	s_waitcnt lgkmcnt(0)
	s_nop 3
	s_waitcnt lgkmcnt(0)
	v_mad_u32_u24 v254, v1, v0, v0
	global_load_dword v0, v165, s[6:7] sc1
	s_waitcnt vmcnt(0)
	v_cmp_lt_u32_e32 vcc, v0, v254
	s_and_saveexec_b64 s[8:9], vcc
	s_cbranch_execz .LBB0_1307
	s_mov_b32 s2, 1
	s_mov_b64 s[10:11], 0
	s_branch .LBB0_1298

.LBB0_1302:
	v_readlane_b32 s6, v239, 61
	v_readlane_b32 s7, v239, 62
	s_add_i32 s2, s2, 1
	s_mov_b64 s[16:17], -1
	s_nop 2
	global_load_dword v0, v165, s[6:7] sc1
	s_waitcnt vmcnt(0)
	v_cmp_ge_u32_e32 vcc, v0, v254
	s_orn2_b64 s[14:15], vcc, exec
	s_branch .LBB0_1297

.LBB0_1311:
	s_or_b64 exec, exec, s[6:7]
	s_waitcnt vmcnt(0)
	v_readfirstlane_b32 s2, v2
	v_cvt_f32_u32_e32 v2, v0
	v_sub_u32_e32 v3, 0, v0
	v_add_u32_e32 v1, s2, v1
	v_readlane_b32 s4, v239, 63
	v_rcp_iflag_f32_e32 v2, v2
	v_readlane_b32 s5, v238, 0
	s_mov_b64 s[8:9], 0
	v_mul_f32_e32 v2, 0x4f7ffffe, v2
	v_cvt_u32_f32_e32 v2, v2
	v_mul_lo_u32 v3, v3, v2
	v_mul_hi_u32 v3, v2, v3
	v_add_u32_e32 v2, v2, v3
	v_mul_hi_u32 v2, v1, v2
	v_mul_lo_u32 v3, v2, v0
	v_sub_u32_e32 v3, v1, v3
	v_cmp_ge_u32_e32 vcc, v3, v0
	v_add_u32_e32 v4, 1, v2
	v_add_u32_e32 v1, 1, v1
	v_cndmask_b32_e32 v2, v2, v4, vcc
	v_sub_u32_e32 v4, v3, v0
	v_cndmask_b32_e32 v3, v3, v4, vcc
	v_cmp_ge_u32_e32 vcc, v3, v0
	v_add_u32_e32 v3, 1, v2
	s_nop 0
	v_cndmask_b32_e32 v2, v2, v3, vcc
	v_mul_lo_u32 v3, v0, v2
	v_add_u32_e32 v0, v3, v0
	v_mov_b32_e32 v255, v0
	v_cmp_ne_u32_e32 vcc, v1, v0
	v_mov_b64_e32 v[0:1], s[4:5]
	s_and_saveexec_b64 s[4:5], vcc
	s_cbranch_execz .LBB0_1323
	v_readlane_b32 s6, v239, 61
	v_readlane_b32 s7, v239, 62
	s_nop 4
	global_load_dword v0, v165, s[6:7] sc1
	s_mov_b64 s[6:7], 0
	s_waitcnt vmcnt(0)
	v_cmp_lt_u32_e32 vcc, v0, v255
	s_and_saveexec_b64 s[8:9], vcc
	s_cbranch_execz .LBB0_1322
	s_mov_b32 s2, 1
	s_mov_b64 s[10:11], 0
	s_branch .LBB0_1315

.LBB0_1319:
	v_readlane_b32 s6, v239, 61
	v_readlane_b32 s7, v239, 62
	s_add_i32 s2, s2, 1
	s_mov_b64 s[16:17], -1
	s_nop 2
	global_load_dword v0, v165, s[6:7] sc1
	s_waitcnt vmcnt(0)
	v_cmp_ge_u32_e32 vcc, v0, v255
	s_orn2_b64 s[14:15], vcc, exec
	s_branch .LBB0_1314

.LBB0_1325:
	s_or_b64 exec, exec, s[4:5]
	s_mov_b64 s[4:5], exec
	v_mbcnt_lo_u32_b32 v0, s4, 0
	v_mbcnt_hi_u32_b32 v0, s5, v0
	v_cmp_eq_u32_e32 vcc, 0, v0
	s_waitcnt vmcnt(0)
	buffer_inv sc1
	s_and_saveexec_b64 s[6:7], vcc
	s_cbranch_execz .LBB0_1327
	s_bcnt1_i32_b64 s2, s[4:5]
	v_readlane_b32 s4, v239, 59
	v_mov_b32_e32 v0, s2
	v_readlane_b32 s5, v239, 60
	s_nop 4
.LBB0_1327:
	s_or_b64 exec, exec, s[6:7]
	s_waitcnt vmcnt(0)

.LBB0_1385:
	s_or_b64 exec, exec, s[4:5]
	s_mov_b64 s[4:5], exec
	v_mbcnt_lo_u32_b32 v0, s4, 0
	v_mbcnt_hi_u32_b32 v0, s5, v0
	v_cmp_eq_u32_e32 vcc, 0, v0
	s_waitcnt vmcnt(0)
	buffer_inv sc1
	s_and_saveexec_b64 s[6:7], vcc
	s_cbranch_execz .LBB0_1387
	s_bcnt1_i32_b64 s2, s[4:5]
	v_readlane_b32 s4, v239, 59
	v_mov_b32_e32 v0, s2
	v_readlane_b32 s5, v239, 60
	s_nop 4
.LBB0_1387:
	s_or_b64 exec, exec, s[6:7]
	s_waitcnt vmcnt(0)

.LBB0_1473:
	s_or_b64 exec, exec, s[4:5]
	s_mov_b64 s[4:5], exec
	v_mbcnt_lo_u32_b32 v0, s4, 0
	v_mbcnt_hi_u32_b32 v0, s5, v0
	v_cmp_eq_u32_e32 vcc, 0, v0
	s_waitcnt vmcnt(0)
	buffer_inv sc1
	s_and_saveexec_b64 s[6:7], vcc
	s_cbranch_execz .LBB0_1475
	s_bcnt1_i32_b64 s2, s[4:5]
	v_readlane_b32 s4, v239, 59
	v_mov_b32_e32 v0, s2
	v_readlane_b32 s5, v239, 60
	s_nop 4
.LBB0_1475:
	s_or_b64 exec, exec, s[6:7]
	s_waitcnt vmcnt(0)

.LBB0_1534:
	s_or_b64 exec, exec, s[4:5]
	s_mov_b64 s[4:5], exec
	v_mbcnt_lo_u32_b32 v0, s4, 0
	v_mbcnt_hi_u32_b32 v0, s5, v0
	v_cmp_eq_u32_e32 vcc, 0, v0
	s_waitcnt vmcnt(0)
	buffer_inv sc1
	s_and_saveexec_b64 s[6:7], vcc
	s_cbranch_execz .LBB0_1536
	s_bcnt1_i32_b64 s2, s[4:5]
	v_readlane_b32 s4, v239, 59
	v_mov_b32_e32 v0, s2
	v_readlane_b32 s5, v239, 60
	s_nop 4
.LBB0_1536:
	s_or_b64 exec, exec, s[6:7]
	s_waitcnt vmcnt(0)

.LBB0_1614:
	s_bcnt1_i32_b64 s2, s[4:5]
	v_readlane_b32 s4, v239, 59
	v_mov_b32_e32 v0, s2
	v_readlane_b32 s5, v239, 60
	s_nop 4
	s_getpc_b64 s[98:99]
